# slot-parity merge roles plus mixers item order reversed (attention first, LRU last) on blocks with id bit 3 set
# speedup vs baseline: 1.0060x; 1.0060x over previous
.LBB0_260:
	s_or_b64 exec, exec, s[8:9]
	v_readlane_b32 s0, v236, 55
	v_readlane_b32 s1, v236, 56
	s_and_b64 vcc, exec, s[0:1]
	s_waitcnt lgkmcnt(0)
	s_barrier
	s_cbranch_vccz .LBB0_120
	v_readlane_b32 s0, v236, 3
	v_readlane_b32 s1, v236, 4
	s_andn2_b64 vcc, exec, s[0:1]
	s_cbranch_vccnz .LBB0_329
	v_readlane_b32 s0, v236, 57
	s_lshl_b32 s30, s0, 1
	v_readlane_b32 s0, v236, 36
	s_mov_b32 s31, s0
	s_bfe_u32 s1, s0, 0x10003
	s_cmpk_lg_i32 s2, 0x200
	s_cselect_b32 s1, 0, s1
	s_lshl_b32 s1, s1, 10
	s_add_i32 s31, s31, s1
	v_readlane_b32 s1, v236, 37
	s_branch .LBB0_265

.LBB0_264:
	s_bfe_u32 s0, s31, 0x10003
	s_cmpk_lg_i32 s2, 0x200
	s_cselect_b32 s0, 0, s0
	s_cmp_eq_u32 s0, 0
	s_cbranch_scc1 .Lmix_fwd
	s_sub_i32 s31, s31, s2
	s_cmp_lt_i32 s31, 0
	s_cbranch_scc1 .LBB0_329
	s_branch .LBB0_265
